# gate/up epilogue: the 8 row scales of a tile read from LDS together at the top instead of one exposed LDS read per 16-row block
# speedup vs baseline: 1.0203x; 1.0083x over previous
.LBB0_795:
	s_andn2_b64 vcc, exec, s[58:59]
	s_cbranch_vccnz .LBB0_797
	ds_read_b32 v140, v143
	ds_read_b32 v215, v143 offset:64
	ds_read_b32 v216, v143 offset:128
	ds_read_b32 v217, v143 offset:192
	ds_read_b32 v218, v143 offset:512
	ds_read_b32 v219, v143 offset:576
	ds_read_b32 v220, v143 offset:640
	ds_read_b32 v221, v143 offset:704

.LBB0_799:
	s_andn2_b64 vcc, exec, s[58:59]
	s_cbranch_vccnz .LBB0_801
	v_mov_b32_e32 v112, v215

.LBB0_803:
	s_andn2_b64 vcc, exec, s[28:29]
	s_cbranch_vccnz .LBB0_805
	v_mov_b32_e32 v96, v216

.LBB0_807:
	s_andn2_b64 vcc, exec, s[28:29]
	s_cbranch_vccnz .LBB0_809
	v_mov_b32_e32 v80, v217

.LBB0_811:
	s_andn2_b64 vcc, exec, s[28:29]
	s_cbranch_vccnz .LBB0_813
	v_mov_b32_e32 v64, v218

.LBB0_815:
	s_andn2_b64 vcc, exec, s[28:29]
	s_cbranch_vccnz .LBB0_817
	v_mov_b32_e32 v48, v219

.LBB0_819:
	s_andn2_b64 vcc, exec, s[28:29]
	s_cbranch_vccnz .LBB0_821
	v_mov_b32_e32 v34, v220

.LBB0_823:
	s_andn2_b64 vcc, exec, s[8:9]
	s_cbranch_vccnz .LBB0_788
	v_mov_b32_e32 v16, v221
	s_branch .LBB0_788
